# FFN-up epilogue DPP pipelining + store-wait relaxation, FFN-up 4x8 tile order, attention loop re-interleave + epilogue gain-load hoist, prep cvt unroll
# speedup vs baseline: 1.0230x; 1.0007x over previous
; __device__ __forceinline__ void dattn_unit(LAS unsigned char* lds, const bf16_t* Qp, const bf16_t* Kp, const bf16_t* Vtp, int qb, bf16_t* Op, const float* lq1, const float* lk1, const float* lq2, const float* lk2, const float* subg, float outscale, int tid) {
;     ...
;     if (c == 0) { const float inv = 1.f / lt; float ss = 0.f;
; #pragma unroll
;         for (int db = 0; db < 4; ++db)
; #pragma unroll
;             for (int i = 0; i < 16; ++i) { const float v = o[db][i] * inv - X[(db * 16 + i) * 64]; o[db][i] = v; ss += v * v; }
.LBB0_238:
	s_cmpk_gt_u32 s3, 0xff
	s_waitcnt lgkmcnt(0)
	s_barrier
	s_cbranch_scc1 .LBB0_210
	v_div_scale_f32 v67, s[2:3], v0, v0, 1.0
	v_rcp_f32_e32 v68, v67
	s_lshl_b64 s[2:3], s[40:41], 12
	v_readlane_b32 s40, v252, 2
	v_lshlrev_b32_e32 v77, 2, v150
	v_fma_f32 v69, -v67, v68, 1.0
	v_fmac_f32_e32 v68, v69, v68
	v_div_scale_f32 v69, vcc, 1.0, v0, 1.0
	v_mul_f32_e32 v70, v69, v68
	v_fma_f32 v71, -v67, v70, v69
	v_fmac_f32_e32 v70, v71, v68
	v_fma_f32 v67, -v67, v70, v69
	v_div_fmas_f32 v67, v67, v68, v70
	ds_read2st64_b32 v[78:79], v66 offset1:1
	ds_read2st64_b32 v[80:81], v66 offset0:2 offset1:3
	ds_read2st64_b32 v[82:83], v66 offset0:4 offset1:5
	ds_read2st64_b32 v[84:85], v66 offset0:6 offset1:7
	ds_read2st64_b32 v[86:87], v66 offset0:8 offset1:9
	ds_read2st64_b32 v[88:89], v66 offset0:10 offset1:11
	ds_read2st64_b32 v[90:91], v66 offset0:12 offset1:13
	ds_read2st64_b32 v[92:93], v66 offset0:14 offset1:15
	ds_read2st64_b32 v[94:95], v66 offset0:16 offset1:17
	ds_read2st64_b32 v[96:97], v66 offset0:18 offset1:19
	ds_read2st64_b32 v[98:99], v66 offset0:20 offset1:21
	ds_read2st64_b32 v[100:101], v66 offset0:22 offset1:23
	ds_read2st64_b32 v[102:103], v66 offset0:24 offset1:25
	ds_read2st64_b32 v[104:105], v66 offset0:26 offset1:27
	ds_read2st64_b32 v[106:107], v66 offset0:28 offset1:29
	ds_read2st64_b32 v[108:109], v66 offset0:30 offset1:31
	ds_read2st64_b32 v[110:111], v66 offset0:32 offset1:33
	ds_read2st64_b32 v[112:113], v66 offset0:34 offset1:35
	ds_read2st64_b32 v[114:115], v66 offset0:36 offset1:37
	ds_read2st64_b32 v[116:117], v66 offset0:38 offset1:39
	ds_read2st64_b32 v[118:119], v66 offset0:40 offset1:41
	ds_read2st64_b32 v[120:121], v66 offset0:42 offset1:43
	ds_read2st64_b32 v[122:123], v66 offset0:44 offset1:45
	ds_read2st64_b32 v[124:125], v66 offset0:46 offset1:47
	ds_read2st64_b32 v[68:69], v66 offset0:58 offset1:59
	ds_read2st64_b32 v[126:127], v66 offset0:48 offset1:49
	ds_read2st64_b32 v[128:129], v66 offset0:50 offset1:51
	ds_read2st64_b32 v[130:131], v66 offset0:52 offset1:53
	ds_read2st64_b32 v[132:133], v66 offset0:54 offset1:55
	ds_read2st64_b32 v[72:73], v66 offset0:60 offset1:61
	ds_read2st64_b32 v[74:75], v66 offset0:62 offset1:63
	ds_read2st64_b32 v[134:135], v66 offset0:56 offset1:57
	v_div_fixup_f32 v0, v67, v0, 1.0
	v_readlane_b32 s46, v252, 8
	v_readlane_b32 s47, v252, 9
	s_waitcnt lgkmcnt(7)
	v_pk_fma_f32 v[68:69], v[12:13], v[0:1], v[68:69] op_sel_hi:[1,0,1] neg_lo:[0,0,1] neg_hi:[0,0,1]
	s_waitcnt lgkmcnt(2)
	v_pk_fma_f32 v[66:67], v[14:15], v[0:1], v[72:73] op_sel_hi:[1,0,1] neg_lo:[0,0,1] neg_hi:[0,0,1]
	v_pk_fma_f32 v[50:51], v[50:51], v[0:1], v[78:79] op_sel_hi:[1,0,1] neg_lo:[0,0,1] neg_hi:[0,0,1]
	v_pk_fma_f32 v[52:53], v[52:53], v[0:1], v[80:81] op_sel_hi:[1,0,1] neg_lo:[0,0,1] neg_hi:[0,0,1]
	v_pk_mul_f32 v[78:79], v[50:51], v[50:51]
	global_load_dwordx4 v[12:15], v77, s[46:47]
	s_waitcnt lgkmcnt(1)
	v_pk_fma_f32 v[16:17], v[16:17], v[0:1], v[74:75] op_sel_hi:[1,0,1] neg_lo:[0,0,1] neg_hi:[0,0,1]
	v_pk_mul_f32 v[80:81], v[52:53], v[52:53]
	v_pk_fma_f32 v[56:57], v[56:57], v[0:1], v[84:85] op_sel_hi:[1,0,1] neg_lo:[0,0,1] neg_hi:[0,0,1]
	v_pk_fma_f32 v[54:55], v[54:55], v[0:1], v[82:83] op_sel_hi:[1,0,1] neg_lo:[0,0,1] neg_hi:[0,0,1]
	v_pk_fma_f32 v[60:61], v[60:61], v[0:1], v[88:89] op_sel_hi:[1,0,1] neg_lo:[0,0,1] neg_hi:[0,0,1]
	v_pk_fma_f32 v[58:59], v[58:59], v[0:1], v[86:87] op_sel_hi:[1,0,1] neg_lo:[0,0,1] neg_hi:[0,0,1]
	v_pk_fma_f32 v[64:65], v[64:65], v[0:1], v[92:93] op_sel_hi:[1,0,1] neg_lo:[0,0,1] neg_hi:[0,0,1]
	v_pk_fma_f32 v[62:63], v[62:63], v[0:1], v[90:91] op_sel_hi:[1,0,1] neg_lo:[0,0,1] neg_hi:[0,0,1]
	v_pk_fma_f32 v[96:97], v[36:37], v[0:1], v[96:97] op_sel_hi:[1,0,1] neg_lo:[0,0,1] neg_hi:[0,0,1]
	v_pk_fma_f32 v[94:95], v[34:35], v[0:1], v[94:95] op_sel_hi:[1,0,1] neg_lo:[0,0,1] neg_hi:[0,0,1]
	v_pk_fma_f32 v[40:41], v[40:41], v[0:1], v[100:101] op_sel_hi:[1,0,1] neg_lo:[0,0,1] neg_hi:[0,0,1]
	v_pk_fma_f32 v[98:99], v[38:39], v[0:1], v[98:99] op_sel_hi:[1,0,1] neg_lo:[0,0,1] neg_hi:[0,0,1]
	v_pk_fma_f32 v[44:45], v[44:45], v[0:1], v[104:105] op_sel_hi:[1,0,1] neg_lo:[0,0,1] neg_hi:[0,0,1]
	v_pk_fma_f32 v[42:43], v[42:43], v[0:1], v[102:103] op_sel_hi:[1,0,1] neg_lo:[0,0,1] neg_hi:[0,0,1]
	v_pk_fma_f32 v[36:37], v[48:49], v[0:1], v[108:109] op_sel_hi:[1,0,1] neg_lo:[0,0,1] neg_hi:[0,0,1]
	v_pk_fma_f32 v[46:47], v[46:47], v[0:1], v[106:107] op_sel_hi:[1,0,1] neg_lo:[0,0,1] neg_hi:[0,0,1]
	v_pk_fma_f32 v[34:35], v[20:21], v[0:1], v[112:113] op_sel_hi:[1,0,1] neg_lo:[0,0,1] neg_hi:[0,0,1]
	v_pk_fma_f32 v[110:111], v[18:19], v[0:1], v[110:111] op_sel_hi:[1,0,1] neg_lo:[0,0,1] neg_hi:[0,0,1]
	v_pk_fma_f32 v[24:25], v[24:25], v[0:1], v[116:117] op_sel_hi:[1,0,1] neg_lo:[0,0,1] neg_hi:[0,0,1]
	v_pk_fma_f32 v[114:115], v[22:23], v[0:1], v[114:115] op_sel_hi:[1,0,1] neg_lo:[0,0,1] neg_hi:[0,0,1]
	v_pk_fma_f32 v[22:23], v[28:29], v[0:1], v[120:121] op_sel_hi:[1,0,1] neg_lo:[0,0,1] neg_hi:[0,0,1]
	v_pk_fma_f32 v[38:39], v[26:27], v[0:1], v[118:119] op_sel_hi:[1,0,1] neg_lo:[0,0,1] neg_hi:[0,0,1]
	v_pk_fma_f32 v[20:21], v[32:33], v[0:1], v[124:125] op_sel_hi:[1,0,1] neg_lo:[0,0,1] neg_hi:[0,0,1]
	v_pk_fma_f32 v[28:29], v[30:31], v[0:1], v[122:123] op_sel_hi:[1,0,1] neg_lo:[0,0,1] neg_hi:[0,0,1]
	v_pk_fma_f32 v[18:19], v[4:5], v[0:1], v[128:129] op_sel_hi:[1,0,1] neg_lo:[0,0,1] neg_hi:[0,0,1]
	v_pk_fma_f32 v[26:27], v[2:3], v[0:1], v[126:127] op_sel_hi:[1,0,1] neg_lo:[0,0,1] neg_hi:[0,0,1]
	v_pk_fma_f32 v[2:3], v[8:9], v[0:1], v[132:133] op_sel_hi:[1,0,1] neg_lo:[0,0,1] neg_hi:[0,0,1]
	v_pk_fma_f32 v[6:7], v[6:7], v[0:1], v[130:131] op_sel_hi:[1,0,1] neg_lo:[0,0,1] neg_hi:[0,0,1]
	s_waitcnt lgkmcnt(0)
; __device__ __forceinline__ unsigned cvt_pk_bf16(float lo, float hi) { const f32x2_t v = {lo, hi}; const bf16x2_t b = __builtin_convertvector(v, bf16x2_t); return __builtin_bit_cast(unsigned, b); }
; __device__ __forceinline__ float lane_shfl(float v, int src_lane) { return __builtin_bit_cast(float, __builtin_amdgcn_ds_bpermute(src_lane << 2, __builtin_bit_cast(int, v))); }
; __device__ __forceinline__ void dattn_unit(LAS unsigned char* lds, const bf16_t* Qp, const bf16_t* Kp, const bf16_t* Vtp, int qb, bf16_t* Op, const float* lq1, const float* lk1, const float* lq2, const float* lk2, const float* subg, float outscale, int tid) {
;     ...
;     if (c == 0) { const float inv = 1.f / lt; float ss = 0.f;
; #pragma unroll
;         for (int db = 0; db < 4; ++db)
; #pragma unroll
;             for (int i = 0; i < 16; ++i) { const float v = o[db][i] * inv - X[(db * 16 + i) * 64]; o[db][i] = v; ss += v * v; }
;         ss += lane_shfl(ss, lane ^ 32);
;         const float rs = outscale * __builtin_amdgcn_rsqf(ss * (1.f / 128.f) + 1e-6f);
;         bf16_t* orow = Op + (size_t)(32 * g + qi) * DM;
; #pragma unroll
;         for (int db = 0; db < 4; ++db)
; #pragma unroll
;             for (int gg = 0; gg < 4; ++gg) { const int d = 32 * db + 8 * gg + 4 * hh; const f32x4 gv = *(const f32x4*)(subg + d);
;                 u32x2 w; w.x = cvt_pk_bf16(o[db][4 * gg + 0] * rs * gv[0], o[db][4 * gg + 1] * rs * gv[1]); w.y = cvt_pk_bf16(o[db][4 * gg + 2] * rs * gv[2], o[db][4 * gg + 3] * rs * gv[3]);
;                 *(u32x2*)(orow + d) = w; } }
	v_pk_fma_f32 v[4:5], v[10:11], v[0:1], v[134:135] op_sel_hi:[1,0,1] neg_lo:[0,0,1] neg_hi:[0,0,1]
	v_add_f32_e32 v0, v78, v79
	v_add_f32_e32 v0, v0, v80
	v_pk_mul_f32 v[82:83], v[54:55], v[54:55]
	v_add_f32_e32 v0, v0, v81
	v_add_f32_e32 v0, v0, v82
	v_pk_mul_f32 v[84:85], v[56:57], v[56:57]
	v_add_f32_e32 v0, v0, v83
	v_add_f32_e32 v0, v0, v84
	v_pk_mul_f32 v[86:87], v[58:59], v[58:59]
	v_add_f32_e32 v0, v0, v85
	v_add_f32_e32 v0, v0, v86
	v_pk_mul_f32 v[88:89], v[60:61], v[60:61]
	v_add_f32_e32 v0, v0, v87
	v_add_f32_e32 v0, v0, v88
	v_pk_mul_f32 v[90:91], v[62:63], v[62:63]
	v_add_f32_e32 v0, v0, v89
	v_add_f32_e32 v0, v0, v90
	v_pk_mul_f32 v[92:93], v[64:65], v[64:65]
	v_add_f32_e32 v0, v0, v91
	v_add_f32_e32 v0, v0, v92
	v_pk_mul_f32 v[138:139], v[94:95], v[94:95]
	v_add_f32_e32 v0, v0, v93
	v_add_f32_e32 v0, v0, v138
	v_pk_mul_f32 v[136:137], v[96:97], v[96:97]
	v_add_f32_e32 v0, v0, v139
	v_add_f32_e32 v0, v0, v136
	v_pk_mul_f32 v[140:141], v[98:99], v[98:99]
	v_add_f32_e32 v0, v0, v137
	v_add_f32_e32 v0, v0, v140
	v_pk_mul_f32 v[100:101], v[40:41], v[40:41]
	v_add_f32_e32 v0, v0, v141
	v_add_f32_e32 v0, v0, v100
	v_pk_mul_f32 v[102:103], v[42:43], v[42:43]
	v_add_f32_e32 v0, v0, v101
	v_add_f32_e32 v0, v0, v102
	v_pk_mul_f32 v[104:105], v[44:45], v[44:45]
	v_add_f32_e32 v0, v0, v103
	v_add_f32_e32 v0, v0, v104
	v_pk_mul_f32 v[106:107], v[46:47], v[46:47]
	v_add_f32_e32 v0, v0, v105
	v_add_f32_e32 v0, v0, v106
	v_pk_mul_f32 v[48:49], v[36:37], v[36:37]
	v_add_f32_e32 v0, v0, v107
	v_add_f32_e32 v0, v0, v48
	v_pk_mul_f32 v[112:113], v[110:111], v[110:111]
	v_add_f32_e32 v0, v0, v49
	v_add_f32_e32 v0, v0, v112
	v_pk_mul_f32 v[108:109], v[34:35], v[34:35]
	v_add_f32_e32 v0, v0, v113
	v_add_f32_e32 v0, v0, v108
	v_pk_mul_f32 v[142:143], v[114:115], v[114:115]
	v_add_f32_e32 v0, v0, v109
	v_add_f32_e32 v0, v0, v142
	v_pk_mul_f32 v[116:117], v[24:25], v[24:25]
	v_add_f32_e32 v0, v0, v143
	v_add_f32_e32 v0, v0, v116
	v_pk_mul_f32 v[118:119], v[38:39], v[38:39]
	v_add_f32_e32 v0, v0, v117
	v_add_f32_e32 v0, v0, v118
	v_pk_mul_f32 v[120:121], v[22:23], v[22:23]
	v_add_f32_e32 v0, v0, v119
	v_add_f32_e32 v0, v0, v120
	v_pk_mul_f32 v[30:31], v[28:29], v[28:29]
	v_add_f32_e32 v0, v0, v121
	v_add_f32_e32 v0, v0, v30
	v_pk_mul_f32 v[32:33], v[20:21], v[20:21]
	v_add_f32_e32 v0, v0, v31
	v_add_f32_e32 v0, v0, v32
	v_pk_mul_f32 v[124:125], v[26:27], v[26:27]
	v_add_f32_e32 v0, v0, v33
	v_add_f32_e32 v0, v0, v124
	v_pk_mul_f32 v[122:123], v[18:19], v[18:19]
	v_add_f32_e32 v0, v0, v125
	v_add_f32_e32 v0, v0, v122
	v_pk_mul_f32 v[126:127], v[6:7], v[6:7]
	v_add_f32_e32 v0, v0, v123
	v_add_f32_e32 v0, v0, v126
	v_pk_mul_f32 v[8:9], v[2:3], v[2:3]
	v_add_f32_e32 v0, v0, v127
	v_add_f32_e32 v0, v0, v8
	v_pk_mul_f32 v[10:11], v[4:5], v[4:5]
	v_add_f32_e32 v0, v0, v9
	v_add_f32_e32 v0, v0, v10
	v_pk_mul_f32 v[70:71], v[68:69], v[68:69]
	v_add_f32_e32 v0, v0, v11
	v_add_f32_e32 v0, v0, v70
	v_pk_mul_f32 v[72:73], v[66:67], v[66:67]
	v_add_f32_e32 v0, v0, v71
	v_add_f32_e32 v0, v0, v72
	v_pk_mul_f32 v[74:75], v[16:17], v[16:17]
	v_add_f32_e32 v0, v0, v73
	v_add_f32_e32 v0, v0, v74
	v_add_f32_e32 v8, v0, v75
	ds_bpermute_b32 v9, v76, v8
	v_readlane_b32 s4, v252, 58
	v_readlane_b32 s5, v252, 59
	s_add_u32 s2, s4, s2
	s_addc_u32 s3, s5, s3
	s_waitcnt lgkmcnt(0)
	v_add_f32_e32 v8, v8, v9
	v_mov_b32_e32 v9, 0x358637bd
	v_fmamk_f32 v8, v8, 0x3c000000, v9
	v_rsq_f32_e32 v10, v8
	s_add_u32 s0, s2, s0
	s_addc_u32 s1, s3, s1
	v_lshlrev_b32_e32 v0, 12, v216
	v_lshl_add_u64 v[8:9], s[0:1], 0, v[0:1]
	v_lshlrev_b32_e32 v0, 1, v150
	v_lshl_add_u64 v[30:31], v[8:9], 0, v[0:1]
	v_mul_f32_e32 v0, 0x3f24fd5c, v10
	v_pk_mul_f32 v[8:9], v[50:51], v[0:1] op_sel_hi:[1,0]
	v_pk_mul_f32 v[10:11], v[52:53], v[0:1] op_sel_hi:[1,0]
	s_waitcnt vmcnt(0)
	v_pk_mul_f32 v[8:9], v[12:13], v[8:9]
	v_pk_mul_f32 v[10:11], v[14:15], v[10:11]
	v_cvt_pk_bf16_f32 v8, v8, v9
	v_cvt_pk_bf16_f32 v9, v10, v11
	global_store_dwordx2 v[30:31], v[8:9], off
	global_load_dwordx4 v[100:103], v77, s[46:47] offset:32
	global_load_dwordx4 v[104:107], v77, s[46:47] offset:64
	global_load_dwordx4 v[116:119], v77, s[46:47] offset:96
	global_load_dwordx4 v[120:123], v77, s[46:47] offset:128
	global_load_dwordx4 v[124:127], v77, s[46:47] offset:160
	global_load_dwordx4 v[128:131], v77, s[46:47] offset:192
	global_load_dwordx4 v[132:135], v77, s[46:47] offset:224
	global_load_dwordx4 v[136:139], v77, s[46:47] offset:256
	global_load_dwordx4 v[140:143], v77, s[46:47] offset:288
	global_load_dwordx4 v[144:147], v77, s[46:47] offset:320
	global_load_dwordx4 v[152:155], v77, s[46:47] offset:352
	global_load_dwordx4 v[156:159], v77, s[46:47] offset:384
	global_load_dwordx4 v[160:163], v77, s[46:47] offset:416
	global_load_dwordx4 v[84:87], v77, s[46:47] offset:448
	global_load_dwordx4 v[88:91], v77, s[46:47] offset:480
	v_pk_mul_f32 v[12:13], v[54:55], v[0:1] op_sel_hi:[1,0]
	v_pk_mul_f32 v[14:15], v[60:61], v[0:1] op_sel_hi:[1,0]
	v_pk_mul_f32 v[6:7], v[6:7], v[0:1] op_sel_hi:[1,0]
	v_pk_mul_f32 v[2:3], v[2:3], v[0:1] op_sel_hi:[1,0]
	v_readlane_b32 s48, v252, 10
	v_readlane_b32 s49, v252, 11
	v_readlane_b32 s50, v252, 12
	v_readlane_b32 s51, v252, 13
	v_readlane_b32 s52, v252, 14
	v_readlane_b32 s53, v252, 15
	v_readlane_b32 s54, v252, 16
	v_readlane_b32 s55, v252, 17
	v_readlane_b32 s50, v255, 12
	v_readlane_b32 s48, v255, 10
	v_readlane_b32 s51, v255, 13
	v_readlane_b32 s49, v255, 11
	v_readlane_b32 s54, v255, 15
	v_readlane_b32 s53, v254, 62
	v_readlane_b32 s52, v254, 61
	v_readlane_b32 s41, v252, 3
	v_readlane_b32 s42, v252, 4
	v_readlane_b32 s43, v252, 5
	v_readlane_b32 s44, v252, 6
	v_readlane_b32 s45, v252, 7
	v_readlane_b32 s55, v255, 16
	s_waitcnt vmcnt(14)
; __device__ __forceinline__ unsigned cvt_pk_bf16(float lo, float hi) { const f32x2_t v = {lo, hi}; const bf16x2_t b = __builtin_convertvector(v, bf16x2_t); return __builtin_bit_cast(unsigned, b); }
; __device__ __forceinline__ void dattn_unit(LAS unsigned char* lds, const bf16_t* Qp, const bf16_t* Kp, const bf16_t* Vtp, int qb, bf16_t* Op, const float* lq1, const float* lk1, const float* lq2, const float* lk2, const float* subg, float outscale, int tid) {
;     ...
;         for (int db = 0; db < 4; ++db)
; #pragma unroll
;             for (int gg = 0; gg < 4; ++gg) { const int d = 32 * db + 8 * gg + 4 * hh; const f32x4 gv = *(const f32x4*)(subg + d);
;                 u32x2 w; w.x = cvt_pk_bf16(o[db][4 * gg + 0] * rs * gv[0], o[db][4 * gg + 1] * rs * gv[1]); w.y = cvt_pk_bf16(o[db][4 * gg + 2] * rs * gv[2], o[db][4 * gg + 3] * rs * gv[3]);
;                 *(u32x2*)(orow + d) = w; } }
	v_pk_mul_f32 v[100:101], v[100:101], v[12:13]
	v_pk_mul_f32 v[12:13], v[56:57], v[0:1] op_sel_hi:[1,0]
	v_cvt_pk_bf16_f32 v100, v100, v101
	v_pk_mul_f32 v[102:103], v[102:103], v[12:13]
	v_pk_mul_f32 v[12:13], v[58:59], v[0:1] op_sel_hi:[1,0]
	v_cvt_pk_bf16_f32 v101, v102, v103
	global_store_dwordx2 v[30:31], v[100:101], off offset:16
	s_waitcnt vmcnt(14)
	v_pk_mul_f32 v[104:105], v[104:105], v[12:13]
	v_pk_mul_f32 v[106:107], v[106:107], v[14:15]
	v_cvt_pk_bf16_f32 v104, v104, v105
	v_cvt_pk_bf16_f32 v105, v106, v107
	global_store_dwordx2 v[30:31], v[104:105], off offset:32
	v_pk_mul_f32 v[12:13], v[62:63], v[0:1] op_sel_hi:[1,0]
	v_pk_mul_f32 v[14:15], v[64:65], v[0:1] op_sel_hi:[1,0]
	s_waitcnt vmcnt(14)
	v_pk_mul_f32 v[116:117], v[116:117], v[12:13]
	v_pk_mul_f32 v[118:119], v[118:119], v[14:15]
	v_cvt_pk_bf16_f32 v116, v116, v117
	v_cvt_pk_bf16_f32 v117, v118, v119
	global_store_dwordx2 v[30:31], v[116:117], off offset:48
	v_pk_mul_f32 v[12:13], v[94:95], v[0:1] op_sel_hi:[1,0]
	v_pk_mul_f32 v[14:15], v[96:97], v[0:1] op_sel_hi:[1,0]
	s_waitcnt vmcnt(14)
	v_pk_mul_f32 v[120:121], v[12:13], v[120:121]
	v_pk_mul_f32 v[122:123], v[14:15], v[122:123]
	v_cvt_pk_bf16_f32 v120, v120, v121
	v_cvt_pk_bf16_f32 v121, v122, v123
	global_store_dwordx2 v[30:31], v[120:121], off offset:64
	v_pk_mul_f32 v[12:13], v[98:99], v[0:1] op_sel_hi:[1,0]
	v_pk_mul_f32 v[14:15], v[40:41], v[0:1] op_sel_hi:[1,0]
	s_waitcnt vmcnt(14)
	v_pk_mul_f32 v[124:125], v[12:13], v[124:125]
	v_pk_mul_f32 v[126:127], v[14:15], v[126:127]
	v_cvt_pk_bf16_f32 v124, v124, v125
	v_cvt_pk_bf16_f32 v125, v126, v127
	global_store_dwordx2 v[30:31], v[124:125], off offset:80
	v_pk_mul_f32 v[12:13], v[42:43], v[0:1] op_sel_hi:[1,0]
	v_pk_mul_f32 v[14:15], v[44:45], v[0:1] op_sel_hi:[1,0]
	s_waitcnt vmcnt(14)
	v_pk_mul_f32 v[128:129], v[12:13], v[128:129]
	v_pk_mul_f32 v[130:131], v[14:15], v[130:131]
	v_cvt_pk_bf16_f32 v128, v128, v129
	v_cvt_pk_bf16_f32 v129, v130, v131
	global_store_dwordx2 v[30:31], v[128:129], off offset:96
	v_pk_mul_f32 v[12:13], v[46:47], v[0:1] op_sel_hi:[1,0]
	v_pk_mul_f32 v[14:15], v[36:37], v[0:1] op_sel_hi:[1,0]
	s_waitcnt vmcnt(14)
	v_pk_mul_f32 v[132:133], v[12:13], v[132:133]
	v_pk_mul_f32 v[134:135], v[14:15], v[134:135]
	v_cvt_pk_bf16_f32 v132, v132, v133
	v_cvt_pk_bf16_f32 v133, v134, v135
	global_store_dwordx2 v[30:31], v[132:133], off offset:112
	v_pk_mul_f32 v[12:13], v[110:111], v[0:1] op_sel_hi:[1,0]
	v_pk_mul_f32 v[14:15], v[34:35], v[0:1] op_sel_hi:[1,0]
	s_waitcnt vmcnt(14)
	v_pk_mul_f32 v[136:137], v[12:13], v[136:137]
	v_pk_mul_f32 v[138:139], v[14:15], v[138:139]
	v_cvt_pk_bf16_f32 v136, v136, v137
	v_cvt_pk_bf16_f32 v137, v138, v139
	global_store_dwordx2 v[30:31], v[136:137], off offset:128
	v_pk_mul_f32 v[12:13], v[114:115], v[0:1] op_sel_hi:[1,0]
	v_pk_mul_f32 v[14:15], v[24:25], v[0:1] op_sel_hi:[1,0]
	s_waitcnt vmcnt(14)
	v_pk_mul_f32 v[140:141], v[12:13], v[140:141]
	v_pk_mul_f32 v[142:143], v[14:15], v[142:143]
	v_cvt_pk_bf16_f32 v140, v140, v141
	v_cvt_pk_bf16_f32 v141, v142, v143
	global_store_dwordx2 v[30:31], v[140:141], off offset:144
	v_pk_mul_f32 v[12:13], v[38:39], v[0:1] op_sel_hi:[1,0]
	v_pk_mul_f32 v[14:15], v[22:23], v[0:1] op_sel_hi:[1,0]
	s_waitcnt vmcnt(14)
	v_pk_mul_f32 v[144:145], v[12:13], v[144:145]
	v_pk_mul_f32 v[146:147], v[14:15], v[146:147]
	v_cvt_pk_bf16_f32 v144, v144, v145
	v_cvt_pk_bf16_f32 v145, v146, v147
	global_store_dwordx2 v[30:31], v[144:145], off offset:160
	v_pk_mul_f32 v[12:13], v[28:29], v[0:1] op_sel_hi:[1,0]
	v_pk_mul_f32 v[14:15], v[20:21], v[0:1] op_sel_hi:[1,0]
	s_waitcnt vmcnt(14)
	v_pk_mul_f32 v[152:153], v[12:13], v[152:153]
	v_pk_mul_f32 v[154:155], v[14:15], v[154:155]
	v_cvt_pk_bf16_f32 v152, v152, v153
	v_cvt_pk_bf16_f32 v153, v154, v155
	global_store_dwordx2 v[30:31], v[152:153], off offset:176
	v_pk_mul_f32 v[12:13], v[26:27], v[0:1] op_sel_hi:[1,0]
	v_pk_mul_f32 v[14:15], v[18:19], v[0:1] op_sel_hi:[1,0]
	s_waitcnt vmcnt(14)
	v_pk_mul_f32 v[156:157], v[12:13], v[156:157]
	v_pk_mul_f32 v[158:159], v[14:15], v[158:159]
	v_cvt_pk_bf16_f32 v156, v156, v157
	v_cvt_pk_bf16_f32 v157, v158, v159
	global_store_dwordx2 v[30:31], v[156:157], off offset:192
	s_waitcnt vmcnt(14)
	v_pk_mul_f32 v[6:7], v[6:7], v[160:161]
	v_pk_mul_f32 v[2:3], v[2:3], v[162:163]
	v_cvt_pk_bf16_f32 v6, v6, v7
	v_cvt_pk_bf16_f32 v7, v2, v3
	global_store_dwordx2 v[30:31], v[6:7], off offset:208
	v_pk_mul_f32 v[2:3], v[4:5], v[0:1] op_sel_hi:[1,0]
	v_pk_mul_f32 v[4:5], v[68:69], v[0:1] op_sel_hi:[1,0]
	s_waitcnt vmcnt(14)
	v_pk_mul_f32 v[2:3], v[2:3], v[84:85]
	v_pk_mul_f32 v[4:5], v[4:5], v[86:87]
	v_cvt_pk_bf16_f32 v2, v2, v3
	v_cvt_pk_bf16_f32 v3, v4, v5
	global_store_dwordx2 v[30:31], v[2:3], off offset:224
	v_pk_mul_f32 v[6:7], v[66:67], v[0:1] op_sel_hi:[1,0]
	v_pk_mul_f32 v[8:9], v[16:17], v[0:1] op_sel_hi:[1,0]
	v_readlane_b32 s46, v254, 63
	v_readlane_b32 s47, v255, 0
	s_waitcnt vmcnt(14)
	v_pk_mul_f32 v[88:89], v[6:7], v[88:89]
	v_pk_mul_f32 v[90:91], v[8:9], v[90:91]
	v_cvt_pk_bf16_f32 v88, v88, v89
	v_cvt_pk_bf16_f32 v89, v90, v91
	global_store_dwordx2 v[30:31], v[88:89], off offset:240
	s_branch .LBB0_210
